# transposes: all 8 tiles of a batch loaded up front (128 load VGPRs), end-of-layer barrier instance also hand-written
# speedup vs baseline: 1.2849x; 1.0018x over previous
.LBB0_45:
	s_and_b32 s26, 0xffff, s37
	v_cvt_f32_u32_e32 v0, s26
	s_and_b32 s26, 0xffff, s36
	v_cvt_f32_u32_e32 v1, s26
	v_mov_b32_e32 v8, v128
	v_rcp_iflag_f32_e32 v2, v0
	v_mov_b32_e32 v4, 0
	v_ashrrev_i32_e32 v9, 4, v8
	v_mul_f32_e32 v2, v1, v2
	v_trunc_f32_e32 v2, v2
	v_cvt_u32_f32_e32 v3, v2
	v_fma_f32 v1, -v2, v0, v1
	v_cmp_ge_f32_e64 s[26:27], |v1|, v0
	s_cmp_lg_u64 s[26:27], 0
	v_readfirstlane_b32 s26, v3
	s_addc_u32 s26, s26, 0
	s_and_b32 s27, s26, 0xffff
	s_mul_i32 s35, s26, s37
	s_lshl_b32 s26, s27, 6
	s_sub_i32 s27, s36, s35
	s_lshl_b32 s27, s27, 6
	v_lshlrev_b32_e32 v0, 2, v8
	s_and_b32 s27, s27, 0xffc0
	v_and_b32_e32 v1, 60, v0
	v_or_b32_e32 v0, s27, v1
	v_lshlrev_b32_e32 v12, 2, v0
	v_cmp_gt_u32_e32 vcc, s0, v0
	v_lshl_add_u64 v[6:7], s[24:25], 0, v[12:13]
	v_lshrrev_b32_e32 v36, 4, v128
	v_and_b32_e32 v37, 15, v128
	v_lshlrev_b32_e32 v37, 2, v37
	s_movk_i32 s50, 0x104
	v_mul_lo_u32 v41, v36, s50
	v_lshl_add_u32 v20, v37, 2, v41
	v_add_u32_e32 v21, 0x1040, v20
	v_add_u32_e32 v22, 0x2080, v20
	v_add_u32_e32 v23, 0x30c0, v20
	v_add_u32_e32 v24, 0x4200, v20
	v_add_u32_e32 v25, 0x4200, v21
	v_add_u32_e32 v26, 0x4200, v22
	v_add_u32_e32 v27, 0x4200, v23
	v_and_b32_e32 v41, 3, v128
	v_lshlrev_b32_e32 v41, 4, v41
	v_mul_lo_u32 v28, v41, s50
	v_and_b32_e32 v42, -4, v128
	v_add_u32_e32 v28, v28, v42
	v_add_u32_e32 v29, 0x400, v28
	v_add_u32_e32 v30, 0x800, v28
	v_add_u32_e32 v31, 0xc00, v28
	v_add_u32_e32 v32, 0x4200, v28
	v_add_u32_e32 v33, 0x4200, v29
	v_add_u32_e32 v34, 0x4200, v30
	v_add_u32_e32 v35, 0x4200, v31
	v_add_u32_e32 v38, s26, v36
	v_mul_lo_u32 v38, v38, s0
	v_lshlrev_b32_e32 v38, 2, v38
	s_lshl_b32 s51, s0, 6
	s_sub_u32 s52, s0, 4
	v_lshrrev_b32_e32 v39, 2, v128
	v_add_u32_e32 v39, s27, v39
	v_mul_lo_u32 v39, v39, s22
	v_add_u32_e32 v39, s26, v39
	v_add_u32_e32 v39, v41, v39
	v_lshlrev_b32_e32 v39, 1, v39
	s_lshl_b32 s53, s22, 7
	v_add_u32_e32 v40, s27, v37
	v_min_u32_e32 v40, s52, v40
	v_lshl_add_u32 v112, v40, 2, v38
	v_add_u32_e32 v113, s51, v112
	v_add_u32_e32 v114, s51, v113
	v_add_u32_e32 v115, s51, v114
	global_load_dwordx4 v[48:51], v112, s[24:25] nt
	global_load_dwordx4 v[52:55], v113, s[24:25] nt
	global_load_dwordx4 v[56:59], v114, s[24:25] nt
	global_load_dwordx4 v[60:63], v115, s[24:25] nt
	v_add_u32_e32 v40, s27, v37
	v_add_u32_e32 v40, 64, v40
	v_min_u32_e32 v40, s52, v40
	v_lshl_add_u32 v112, v40, 2, v38
	v_add_u32_e32 v113, s51, v112
	v_add_u32_e32 v114, s51, v113
	v_add_u32_e32 v115, s51, v114
	global_load_dwordx4 v[64:67], v112, s[24:25] nt
	global_load_dwordx4 v[68:71], v113, s[24:25] nt
	global_load_dwordx4 v[72:75], v114, s[24:25] nt
	global_load_dwordx4 v[76:79], v115, s[24:25] nt
	v_add_u32_e32 v40, s27, v37
	v_add_u32_e32 v40, 128, v40
	v_min_u32_e32 v40, s52, v40
	v_lshl_add_u32 v112, v40, 2, v38
	v_add_u32_e32 v113, s51, v112
	v_add_u32_e32 v114, s51, v113
	v_add_u32_e32 v115, s51, v114
	global_load_dwordx4 v[80:83], v112, s[24:25] nt
	global_load_dwordx4 v[84:87], v113, s[24:25] nt
	global_load_dwordx4 v[88:91], v114, s[24:25] nt
	global_load_dwordx4 v[92:95], v115, s[24:25] nt
	v_add_u32_e32 v40, s27, v37
	v_add_u32_e32 v40, 192, v40
	v_min_u32_e32 v40, s52, v40
	v_lshl_add_u32 v112, v40, 2, v38
	v_add_u32_e32 v113, s51, v112
	v_add_u32_e32 v114, s51, v113
	v_add_u32_e32 v115, s51, v114
	global_load_dwordx4 v[96:99], v112, s[24:25] nt
	global_load_dwordx4 v[100:103], v113, s[24:25] nt
	global_load_dwordx4 v[104:107], v114, s[24:25] nt
	global_load_dwordx4 v[108:111], v115, s[24:25] nt
	v_add_u32_e32 v40, s27, v37
	v_add_u32_e32 v40, 256, v40
	v_min_u32_e32 v40, s52, v40
	v_lshl_add_u32 v112, v40, 2, v38
	v_add_u32_e32 v113, s51, v112
	v_add_u32_e32 v114, s51, v113
	v_add_u32_e32 v115, s51, v114
	global_load_dwordx4 v[168:171], v112, s[24:25] nt
	global_load_dwordx4 v[172:175], v113, s[24:25] nt
	global_load_dwordx4 v[176:179], v114, s[24:25] nt
	global_load_dwordx4 v[180:183], v115, s[24:25] nt
	v_add_u32_e32 v40, s27, v37
	v_add_u32_e32 v40, 320, v40
	v_min_u32_e32 v40, s52, v40
	v_lshl_add_u32 v112, v40, 2, v38
	v_add_u32_e32 v113, s51, v112
	v_add_u32_e32 v114, s51, v113
	v_add_u32_e32 v115, s51, v114
	global_load_dwordx4 v[184:187], v112, s[24:25] nt
	global_load_dwordx4 v[188:191], v113, s[24:25] nt
	global_load_dwordx4 v[192:195], v114, s[24:25] nt
	global_load_dwordx4 v[196:199], v115, s[24:25] nt
	v_add_u32_e32 v40, s27, v37
	v_add_u32_e32 v40, 384, v40
	v_min_u32_e32 v40, s52, v40
	v_lshl_add_u32 v112, v40, 2, v38
	v_add_u32_e32 v113, s51, v112
	v_add_u32_e32 v114, s51, v113
	v_add_u32_e32 v115, s51, v114
	global_load_dwordx4 v[200:203], v112, s[24:25] nt
	global_load_dwordx4 v[204:207], v113, s[24:25] nt
	global_load_dwordx4 v[208:211], v114, s[24:25] nt
	global_load_dwordx4 v[212:215], v115, s[24:25] nt
	v_add_u32_e32 v40, s27, v37
	v_add_u32_e32 v40, 448, v40
	v_min_u32_e32 v40, s52, v40
	v_lshl_add_u32 v112, v40, 2, v38
	v_add_u32_e32 v113, s51, v112
	v_add_u32_e32 v114, s51, v113
	v_add_u32_e32 v115, s51, v114
	global_load_dwordx4 v[216:219], v112, s[24:25] nt
	global_load_dwordx4 v[220:223], v113, s[24:25] nt
	global_load_dwordx4 v[224:227], v114, s[24:25] nt
	global_load_dwordx4 v[228:231], v115, s[24:25] nt
	s_waitcnt vmcnt(28)
	v_add_u32_e32 v40, s27, v37
	v_cmp_gt_u32_e32 vcc, s0, v40
	s_nop 1
	v_cndmask_b32_e32 v48, 0, v48, vcc
	v_cndmask_b32_e32 v49, 0, v49, vcc
	v_cndmask_b32_e32 v50, 0, v50, vcc
	v_cndmask_b32_e32 v51, 0, v51, vcc
	v_cndmask_b32_e32 v52, 0, v52, vcc
	v_cndmask_b32_e32 v53, 0, v53, vcc
	v_cndmask_b32_e32 v54, 0, v54, vcc
	v_cndmask_b32_e32 v55, 0, v55, vcc
	v_cndmask_b32_e32 v56, 0, v56, vcc
	v_cndmask_b32_e32 v57, 0, v57, vcc
	v_cndmask_b32_e32 v58, 0, v58, vcc
	v_cndmask_b32_e32 v59, 0, v59, vcc
	v_cndmask_b32_e32 v60, 0, v60, vcc
	v_cndmask_b32_e32 v61, 0, v61, vcc
	v_cndmask_b32_e32 v62, 0, v62, vcc
	v_cndmask_b32_e32 v63, 0, v63, vcc
	ds_write2_b32 v20, v48, v49 offset1:1
	ds_write2_b32 v20, v50, v51 offset0:2 offset1:3
	ds_write2_b32 v21, v52, v53 offset1:1
	ds_write2_b32 v21, v54, v55 offset0:2 offset1:3
	ds_write2_b32 v22, v56, v57 offset1:1
	ds_write2_b32 v22, v58, v59 offset0:2 offset1:3
	ds_write2_b32 v23, v60, v61 offset1:1
	ds_write2_b32 v23, v62, v63 offset0:2 offset1:3
	s_waitcnt lgkmcnt(0)
	s_barrier
	ds_read2_b32 v[232:233], v28 offset0:0 offset1:65
	ds_read2_b32 v[234:235], v28 offset0:130 offset1:195
	ds_read2_b32 v[236:237], v29 offset0:4 offset1:69
	ds_read2_b32 v[238:239], v29 offset0:134 offset1:199
	ds_read2_b32 v[240:241], v30 offset0:8 offset1:73
	ds_read2_b32 v[242:243], v30 offset0:138 offset1:203
	ds_read2_b32 v[244:245], v31 offset0:12 offset1:77
	ds_read2_b32 v[246:247], v31 offset0:142 offset1:207
	s_waitcnt lgkmcnt(0)
	v_cvt_pk_bf16_f32 v248, v232, v233
	v_cvt_pk_bf16_f32 v249, v234, v235
	v_cvt_pk_bf16_f32 v250, v236, v237
	v_cvt_pk_bf16_f32 v251, v238, v239
	v_cvt_pk_bf16_f32 v252, v240, v241
	v_cvt_pk_bf16_f32 v253, v242, v243
	v_cvt_pk_bf16_f32 v254, v244, v245
	v_cvt_pk_bf16_f32 v255, v246, v247
	global_store_dwordx4 v39, v[248:251], s[20:21]
	global_store_dwordx4 v39, v[252:255], s[20:21] offset:16
	v_add_u32_e32 v39, s53, v39
	s_waitcnt vmcnt(26)
	v_add_u32_e32 v40, s27, v37
	v_add_u32_e32 v40, 64, v40
	v_cmp_gt_u32_e32 vcc, s0, v40
	s_nop 1
	v_cndmask_b32_e32 v64, 0, v64, vcc
	v_cndmask_b32_e32 v65, 0, v65, vcc
	v_cndmask_b32_e32 v66, 0, v66, vcc
	v_cndmask_b32_e32 v67, 0, v67, vcc
	v_cndmask_b32_e32 v68, 0, v68, vcc
	v_cndmask_b32_e32 v69, 0, v69, vcc
	v_cndmask_b32_e32 v70, 0, v70, vcc
	v_cndmask_b32_e32 v71, 0, v71, vcc
	v_cndmask_b32_e32 v72, 0, v72, vcc
	v_cndmask_b32_e32 v73, 0, v73, vcc
	v_cndmask_b32_e32 v74, 0, v74, vcc
	v_cndmask_b32_e32 v75, 0, v75, vcc
	v_cndmask_b32_e32 v76, 0, v76, vcc
	v_cndmask_b32_e32 v77, 0, v77, vcc
	v_cndmask_b32_e32 v78, 0, v78, vcc
	v_cndmask_b32_e32 v79, 0, v79, vcc
	ds_write2_b32 v24, v64, v65 offset1:1
	ds_write2_b32 v24, v66, v67 offset0:2 offset1:3
	ds_write2_b32 v25, v68, v69 offset1:1
	ds_write2_b32 v25, v70, v71 offset0:2 offset1:3
	ds_write2_b32 v26, v72, v73 offset1:1
	ds_write2_b32 v26, v74, v75 offset0:2 offset1:3
	ds_write2_b32 v27, v76, v77 offset1:1
	ds_write2_b32 v27, v78, v79 offset0:2 offset1:3
	s_waitcnt lgkmcnt(0)
	s_barrier
	ds_read2_b32 v[232:233], v32 offset0:0 offset1:65
	ds_read2_b32 v[234:235], v32 offset0:130 offset1:195
	ds_read2_b32 v[236:237], v33 offset0:4 offset1:69
	ds_read2_b32 v[238:239], v33 offset0:134 offset1:199
	ds_read2_b32 v[240:241], v34 offset0:8 offset1:73
	ds_read2_b32 v[242:243], v34 offset0:138 offset1:203
	ds_read2_b32 v[244:245], v35 offset0:12 offset1:77
	ds_read2_b32 v[246:247], v35 offset0:142 offset1:207
	s_waitcnt lgkmcnt(0)
	v_cvt_pk_bf16_f32 v248, v232, v233
	v_cvt_pk_bf16_f32 v249, v234, v235
	v_cvt_pk_bf16_f32 v250, v236, v237
	v_cvt_pk_bf16_f32 v251, v238, v239
	v_cvt_pk_bf16_f32 v252, v240, v241
	v_cvt_pk_bf16_f32 v253, v242, v243
	v_cvt_pk_bf16_f32 v254, v244, v245
	v_cvt_pk_bf16_f32 v255, v246, v247
	global_store_dwordx4 v39, v[248:251], s[20:21]
	global_store_dwordx4 v39, v[252:255], s[20:21] offset:16
	v_add_u32_e32 v39, s53, v39
	s_waitcnt vmcnt(24)
	v_add_u32_e32 v40, s27, v37
	v_add_u32_e32 v40, 128, v40
	v_cmp_gt_u32_e32 vcc, s0, v40
	s_nop 1
	v_cndmask_b32_e32 v80, 0, v80, vcc
	v_cndmask_b32_e32 v81, 0, v81, vcc
	v_cndmask_b32_e32 v82, 0, v82, vcc
	v_cndmask_b32_e32 v83, 0, v83, vcc
	v_cndmask_b32_e32 v84, 0, v84, vcc
	v_cndmask_b32_e32 v85, 0, v85, vcc
	v_cndmask_b32_e32 v86, 0, v86, vcc
	v_cndmask_b32_e32 v87, 0, v87, vcc
	v_cndmask_b32_e32 v88, 0, v88, vcc
	v_cndmask_b32_e32 v89, 0, v89, vcc
	v_cndmask_b32_e32 v90, 0, v90, vcc
	v_cndmask_b32_e32 v91, 0, v91, vcc
	v_cndmask_b32_e32 v92, 0, v92, vcc
	v_cndmask_b32_e32 v93, 0, v93, vcc
	v_cndmask_b32_e32 v94, 0, v94, vcc
	v_cndmask_b32_e32 v95, 0, v95, vcc
	ds_write2_b32 v20, v80, v81 offset1:1
	ds_write2_b32 v20, v82, v83 offset0:2 offset1:3
	ds_write2_b32 v21, v84, v85 offset1:1
	ds_write2_b32 v21, v86, v87 offset0:2 offset1:3
	ds_write2_b32 v22, v88, v89 offset1:1
	ds_write2_b32 v22, v90, v91 offset0:2 offset1:3
	ds_write2_b32 v23, v92, v93 offset1:1
	ds_write2_b32 v23, v94, v95 offset0:2 offset1:3
	s_waitcnt lgkmcnt(0)
	s_barrier
	ds_read2_b32 v[232:233], v28 offset0:0 offset1:65
	ds_read2_b32 v[234:235], v28 offset0:130 offset1:195
	ds_read2_b32 v[236:237], v29 offset0:4 offset1:69
	ds_read2_b32 v[238:239], v29 offset0:134 offset1:199
	ds_read2_b32 v[240:241], v30 offset0:8 offset1:73
	ds_read2_b32 v[242:243], v30 offset0:138 offset1:203
	ds_read2_b32 v[244:245], v31 offset0:12 offset1:77
	ds_read2_b32 v[246:247], v31 offset0:142 offset1:207
	s_waitcnt lgkmcnt(0)
	v_cvt_pk_bf16_f32 v248, v232, v233
	v_cvt_pk_bf16_f32 v249, v234, v235
	v_cvt_pk_bf16_f32 v250, v236, v237
	v_cvt_pk_bf16_f32 v251, v238, v239
	v_cvt_pk_bf16_f32 v252, v240, v241
	v_cvt_pk_bf16_f32 v253, v242, v243
	v_cvt_pk_bf16_f32 v254, v244, v245
	v_cvt_pk_bf16_f32 v255, v246, v247
	global_store_dwordx4 v39, v[248:251], s[20:21]
	global_store_dwordx4 v39, v[252:255], s[20:21] offset:16
	v_add_u32_e32 v39, s53, v39
	s_waitcnt vmcnt(22)
	v_add_u32_e32 v40, s27, v37
	v_add_u32_e32 v40, 192, v40
	v_cmp_gt_u32_e32 vcc, s0, v40
	s_nop 1
	v_cndmask_b32_e32 v96, 0, v96, vcc
	v_cndmask_b32_e32 v97, 0, v97, vcc
	v_cndmask_b32_e32 v98, 0, v98, vcc
	v_cndmask_b32_e32 v99, 0, v99, vcc
	v_cndmask_b32_e32 v100, 0, v100, vcc
	v_cndmask_b32_e32 v101, 0, v101, vcc
	v_cndmask_b32_e32 v102, 0, v102, vcc
	v_cndmask_b32_e32 v103, 0, v103, vcc
	v_cndmask_b32_e32 v104, 0, v104, vcc
	v_cndmask_b32_e32 v105, 0, v105, vcc
	v_cndmask_b32_e32 v106, 0, v106, vcc
	v_cndmask_b32_e32 v107, 0, v107, vcc
	v_cndmask_b32_e32 v108, 0, v108, vcc
	v_cndmask_b32_e32 v109, 0, v109, vcc
	v_cndmask_b32_e32 v110, 0, v110, vcc
	v_cndmask_b32_e32 v111, 0, v111, vcc
	ds_write2_b32 v24, v96, v97 offset1:1
	ds_write2_b32 v24, v98, v99 offset0:2 offset1:3
	ds_write2_b32 v25, v100, v101 offset1:1
	ds_write2_b32 v25, v102, v103 offset0:2 offset1:3
	ds_write2_b32 v26, v104, v105 offset1:1
	ds_write2_b32 v26, v106, v107 offset0:2 offset1:3
	ds_write2_b32 v27, v108, v109 offset1:1
	ds_write2_b32 v27, v110, v111 offset0:2 offset1:3
	s_waitcnt lgkmcnt(0)
	s_barrier
	ds_read2_b32 v[232:233], v32 offset0:0 offset1:65
	ds_read2_b32 v[234:235], v32 offset0:130 offset1:195
	ds_read2_b32 v[236:237], v33 offset0:4 offset1:69
	ds_read2_b32 v[238:239], v33 offset0:134 offset1:199
	ds_read2_b32 v[240:241], v34 offset0:8 offset1:73
	ds_read2_b32 v[242:243], v34 offset0:138 offset1:203
	ds_read2_b32 v[244:245], v35 offset0:12 offset1:77
	ds_read2_b32 v[246:247], v35 offset0:142 offset1:207
	s_waitcnt lgkmcnt(0)
	v_cvt_pk_bf16_f32 v248, v232, v233
	v_cvt_pk_bf16_f32 v249, v234, v235
	v_cvt_pk_bf16_f32 v250, v236, v237
	v_cvt_pk_bf16_f32 v251, v238, v239
	v_cvt_pk_bf16_f32 v252, v240, v241
	v_cvt_pk_bf16_f32 v253, v242, v243
	v_cvt_pk_bf16_f32 v254, v244, v245
	v_cvt_pk_bf16_f32 v255, v246, v247
	global_store_dwordx4 v39, v[248:251], s[20:21]
	global_store_dwordx4 v39, v[252:255], s[20:21] offset:16
	v_add_u32_e32 v39, s53, v39
	s_waitcnt vmcnt(20)
	v_add_u32_e32 v40, s27, v37
	v_add_u32_e32 v40, 256, v40
	v_cmp_gt_u32_e32 vcc, s0, v40
	s_nop 1
	v_cndmask_b32_e32 v168, 0, v168, vcc
	v_cndmask_b32_e32 v169, 0, v169, vcc
	v_cndmask_b32_e32 v170, 0, v170, vcc
	v_cndmask_b32_e32 v171, 0, v171, vcc
	v_cndmask_b32_e32 v172, 0, v172, vcc
	v_cndmask_b32_e32 v173, 0, v173, vcc
	v_cndmask_b32_e32 v174, 0, v174, vcc
	v_cndmask_b32_e32 v175, 0, v175, vcc
	v_cndmask_b32_e32 v176, 0, v176, vcc
	v_cndmask_b32_e32 v177, 0, v177, vcc
	v_cndmask_b32_e32 v178, 0, v178, vcc
	v_cndmask_b32_e32 v179, 0, v179, vcc
	v_cndmask_b32_e32 v180, 0, v180, vcc
	v_cndmask_b32_e32 v181, 0, v181, vcc
	v_cndmask_b32_e32 v182, 0, v182, vcc
	v_cndmask_b32_e32 v183, 0, v183, vcc
	ds_write2_b32 v20, v168, v169 offset1:1
	ds_write2_b32 v20, v170, v171 offset0:2 offset1:3
	ds_write2_b32 v21, v172, v173 offset1:1
	ds_write2_b32 v21, v174, v175 offset0:2 offset1:3
	ds_write2_b32 v22, v176, v177 offset1:1
	ds_write2_b32 v22, v178, v179 offset0:2 offset1:3
	ds_write2_b32 v23, v180, v181 offset1:1
	ds_write2_b32 v23, v182, v183 offset0:2 offset1:3
	s_waitcnt lgkmcnt(0)
	s_barrier
	ds_read2_b32 v[232:233], v28 offset0:0 offset1:65
	ds_read2_b32 v[234:235], v28 offset0:130 offset1:195
	ds_read2_b32 v[236:237], v29 offset0:4 offset1:69
	ds_read2_b32 v[238:239], v29 offset0:134 offset1:199
	ds_read2_b32 v[240:241], v30 offset0:8 offset1:73
	ds_read2_b32 v[242:243], v30 offset0:138 offset1:203
	ds_read2_b32 v[244:245], v31 offset0:12 offset1:77
	ds_read2_b32 v[246:247], v31 offset0:142 offset1:207
	s_waitcnt lgkmcnt(0)
	v_cvt_pk_bf16_f32 v248, v232, v233
	v_cvt_pk_bf16_f32 v249, v234, v235
	v_cvt_pk_bf16_f32 v250, v236, v237
	v_cvt_pk_bf16_f32 v251, v238, v239
	v_cvt_pk_bf16_f32 v252, v240, v241
	v_cvt_pk_bf16_f32 v253, v242, v243
	v_cvt_pk_bf16_f32 v254, v244, v245
	v_cvt_pk_bf16_f32 v255, v246, v247
	global_store_dwordx4 v39, v[248:251], s[20:21]
	global_store_dwordx4 v39, v[252:255], s[20:21] offset:16
	v_add_u32_e32 v39, s53, v39
	s_waitcnt vmcnt(18)
	v_add_u32_e32 v40, s27, v37
	v_add_u32_e32 v40, 320, v40
	v_cmp_gt_u32_e32 vcc, s0, v40
	s_nop 1
	v_cndmask_b32_e32 v184, 0, v184, vcc
	v_cndmask_b32_e32 v185, 0, v185, vcc
	v_cndmask_b32_e32 v186, 0, v186, vcc
	v_cndmask_b32_e32 v187, 0, v187, vcc
	v_cndmask_b32_e32 v188, 0, v188, vcc
	v_cndmask_b32_e32 v189, 0, v189, vcc
	v_cndmask_b32_e32 v190, 0, v190, vcc
	v_cndmask_b32_e32 v191, 0, v191, vcc
	v_cndmask_b32_e32 v192, 0, v192, vcc
	v_cndmask_b32_e32 v193, 0, v193, vcc
	v_cndmask_b32_e32 v194, 0, v194, vcc
	v_cndmask_b32_e32 v195, 0, v195, vcc
	v_cndmask_b32_e32 v196, 0, v196, vcc
	v_cndmask_b32_e32 v197, 0, v197, vcc
	v_cndmask_b32_e32 v198, 0, v198, vcc
	v_cndmask_b32_e32 v199, 0, v199, vcc
	ds_write2_b32 v24, v184, v185 offset1:1
	ds_write2_b32 v24, v186, v187 offset0:2 offset1:3
	ds_write2_b32 v25, v188, v189 offset1:1
	ds_write2_b32 v25, v190, v191 offset0:2 offset1:3
	ds_write2_b32 v26, v192, v193 offset1:1
	ds_write2_b32 v26, v194, v195 offset0:2 offset1:3
	ds_write2_b32 v27, v196, v197 offset1:1
	ds_write2_b32 v27, v198, v199 offset0:2 offset1:3
	s_waitcnt lgkmcnt(0)
	s_barrier
	ds_read2_b32 v[232:233], v32 offset0:0 offset1:65
	ds_read2_b32 v[234:235], v32 offset0:130 offset1:195
	ds_read2_b32 v[236:237], v33 offset0:4 offset1:69
	ds_read2_b32 v[238:239], v33 offset0:134 offset1:199
	ds_read2_b32 v[240:241], v34 offset0:8 offset1:73
	ds_read2_b32 v[242:243], v34 offset0:138 offset1:203
	ds_read2_b32 v[244:245], v35 offset0:12 offset1:77
	ds_read2_b32 v[246:247], v35 offset0:142 offset1:207
	s_waitcnt lgkmcnt(0)
	v_cvt_pk_bf16_f32 v248, v232, v233
	v_cvt_pk_bf16_f32 v249, v234, v235
	v_cvt_pk_bf16_f32 v250, v236, v237
	v_cvt_pk_bf16_f32 v251, v238, v239
	v_cvt_pk_bf16_f32 v252, v240, v241
	v_cvt_pk_bf16_f32 v253, v242, v243
	v_cvt_pk_bf16_f32 v254, v244, v245
	v_cvt_pk_bf16_f32 v255, v246, v247
	global_store_dwordx4 v39, v[248:251], s[20:21]
	global_store_dwordx4 v39, v[252:255], s[20:21] offset:16
	v_add_u32_e32 v39, s53, v39
	s_waitcnt vmcnt(16)
	v_add_u32_e32 v40, s27, v37
	v_add_u32_e32 v40, 384, v40
	v_cmp_gt_u32_e32 vcc, s0, v40
	s_nop 1
	v_cndmask_b32_e32 v200, 0, v200, vcc
	v_cndmask_b32_e32 v201, 0, v201, vcc
	v_cndmask_b32_e32 v202, 0, v202, vcc
	v_cndmask_b32_e32 v203, 0, v203, vcc
	v_cndmask_b32_e32 v204, 0, v204, vcc
	v_cndmask_b32_e32 v205, 0, v205, vcc
	v_cndmask_b32_e32 v206, 0, v206, vcc
	v_cndmask_b32_e32 v207, 0, v207, vcc
	v_cndmask_b32_e32 v208, 0, v208, vcc
	v_cndmask_b32_e32 v209, 0, v209, vcc
	v_cndmask_b32_e32 v210, 0, v210, vcc
	v_cndmask_b32_e32 v211, 0, v211, vcc
	v_cndmask_b32_e32 v212, 0, v212, vcc
	v_cndmask_b32_e32 v213, 0, v213, vcc
	v_cndmask_b32_e32 v214, 0, v214, vcc
	v_cndmask_b32_e32 v215, 0, v215, vcc
	ds_write2_b32 v20, v200, v201 offset1:1
	ds_write2_b32 v20, v202, v203 offset0:2 offset1:3
	ds_write2_b32 v21, v204, v205 offset1:1
	ds_write2_b32 v21, v206, v207 offset0:2 offset1:3
	ds_write2_b32 v22, v208, v209 offset1:1
	ds_write2_b32 v22, v210, v211 offset0:2 offset1:3
	ds_write2_b32 v23, v212, v213 offset1:1
	ds_write2_b32 v23, v214, v215 offset0:2 offset1:3
	s_waitcnt lgkmcnt(0)
	s_barrier
	ds_read2_b32 v[232:233], v28 offset0:0 offset1:65
	ds_read2_b32 v[234:235], v28 offset0:130 offset1:195
	ds_read2_b32 v[236:237], v29 offset0:4 offset1:69
	ds_read2_b32 v[238:239], v29 offset0:134 offset1:199
	ds_read2_b32 v[240:241], v30 offset0:8 offset1:73
	ds_read2_b32 v[242:243], v30 offset0:138 offset1:203
	ds_read2_b32 v[244:245], v31 offset0:12 offset1:77
	ds_read2_b32 v[246:247], v31 offset0:142 offset1:207
	s_waitcnt lgkmcnt(0)
	v_cvt_pk_bf16_f32 v248, v232, v233
	v_cvt_pk_bf16_f32 v249, v234, v235
	v_cvt_pk_bf16_f32 v250, v236, v237
	v_cvt_pk_bf16_f32 v251, v238, v239
	v_cvt_pk_bf16_f32 v252, v240, v241
	v_cvt_pk_bf16_f32 v253, v242, v243
	v_cvt_pk_bf16_f32 v254, v244, v245
	v_cvt_pk_bf16_f32 v255, v246, v247
	global_store_dwordx4 v39, v[248:251], s[20:21]
	global_store_dwordx4 v39, v[252:255], s[20:21] offset:16
	v_add_u32_e32 v39, s53, v39
	s_waitcnt vmcnt(14)
	v_add_u32_e32 v40, s27, v37
	v_add_u32_e32 v40, 448, v40
	v_cmp_gt_u32_e32 vcc, s0, v40
	s_nop 1
	v_cndmask_b32_e32 v216, 0, v216, vcc
	v_cndmask_b32_e32 v217, 0, v217, vcc
	v_cndmask_b32_e32 v218, 0, v218, vcc
	v_cndmask_b32_e32 v219, 0, v219, vcc
	v_cndmask_b32_e32 v220, 0, v220, vcc
	v_cndmask_b32_e32 v221, 0, v221, vcc
	v_cndmask_b32_e32 v222, 0, v222, vcc
	v_cndmask_b32_e32 v223, 0, v223, vcc
	v_cndmask_b32_e32 v224, 0, v224, vcc
	v_cndmask_b32_e32 v225, 0, v225, vcc
	v_cndmask_b32_e32 v226, 0, v226, vcc
	v_cndmask_b32_e32 v227, 0, v227, vcc
	v_cndmask_b32_e32 v228, 0, v228, vcc
	v_cndmask_b32_e32 v229, 0, v229, vcc
	v_cndmask_b32_e32 v230, 0, v230, vcc
	v_cndmask_b32_e32 v231, 0, v231, vcc
	ds_write2_b32 v24, v216, v217 offset1:1
	ds_write2_b32 v24, v218, v219 offset0:2 offset1:3
	ds_write2_b32 v25, v220, v221 offset1:1
	ds_write2_b32 v25, v222, v223 offset0:2 offset1:3
	ds_write2_b32 v26, v224, v225 offset1:1
	ds_write2_b32 v26, v226, v227 offset0:2 offset1:3
	ds_write2_b32 v27, v228, v229 offset1:1
	ds_write2_b32 v27, v230, v231 offset0:2 offset1:3
	s_waitcnt lgkmcnt(0)
	s_barrier
	ds_read2_b32 v[232:233], v32 offset0:0 offset1:65
	ds_read2_b32 v[234:235], v32 offset0:130 offset1:195
	ds_read2_b32 v[236:237], v33 offset0:4 offset1:69
	ds_read2_b32 v[238:239], v33 offset0:134 offset1:199
	ds_read2_b32 v[240:241], v34 offset0:8 offset1:73
	ds_read2_b32 v[242:243], v34 offset0:138 offset1:203
	ds_read2_b32 v[244:245], v35 offset0:12 offset1:77
	ds_read2_b32 v[246:247], v35 offset0:142 offset1:207
	s_waitcnt lgkmcnt(0)
	v_cvt_pk_bf16_f32 v248, v232, v233
	v_cvt_pk_bf16_f32 v249, v234, v235
	v_cvt_pk_bf16_f32 v250, v236, v237
	v_cvt_pk_bf16_f32 v251, v238, v239
	v_cvt_pk_bf16_f32 v252, v240, v241
	v_cvt_pk_bf16_f32 v253, v242, v243
	v_cvt_pk_bf16_f32 v254, v244, v245
	v_cvt_pk_bf16_f32 v255, v246, v247
	global_store_dwordx4 v39, v[248:251], s[20:21]
	global_store_dwordx4 v39, v[252:255], s[20:21] offset:16
	s_waitcnt lgkmcnt(0)
	s_barrier
	s_mov_b64 s[20:21], 0
	s_branch .LBB0_54

.LBB0_185:
	s_mul_i32 s0, s47, s46
	s_mul_i32 s0, s0, s33
	s_lshr_b32 s2, s46, 3
	v_writelane_b32 v163, s0, 19
	s_add_u32 s0, s84, 0x200
	s_addc_u32 s1, s85, 0
	v_writelane_b32 v163, s0, 20
	s_mov_b32 s37, 0
	v_mbcnt_lo_u32_b32 v0, -1, 0
	v_writelane_b32 v163, s1, 21
	s_add_u32 s0, s84, 0x1000
	s_addc_u32 s1, s85, 0
	v_writelane_b32 v163, s0, 22
	v_mov_b32_e32 v117, 0
	v_mov_b32_e32 v129, 1
	v_writelane_b32 v163, s1, 23
	s_add_u32 s0, s84, 0x1100
	s_addc_u32 s1, s85, 0
	v_writelane_b32 v163, s0, 24
	v_mov_b32_e32 v130, 0x358637bd
	v_mov_b32_e32 v131, 0x3ca908c9
	v_writelane_b32 v163, s1, 25
	s_add_u32 s0, s84, 0x1200
	s_addc_u32 s1, s85, 0
	v_writelane_b32 v163, s0, 26
	v_mov_b32_e32 v132, 0x3a27c5ac
	v_mbcnt_hi_u32_b32 v133, -1, v0
	v_writelane_b32 v163, s1, 27
	s_add_u32 s0, s84, 0x1300
	s_addc_u32 s1, s85, 0
	v_writelane_b32 v163, s0, 28
	s_cmp_eq_u32 s40, 15
	v_mov_b32_e32 v134, 0x7f800000
	v_writelane_b32 v163, s1, 29
	s_cselect_b64 s[0:1], -1, 0
	v_writelane_b32 v163, s0, 30
	s_cmp_eq_u32 s40, 14
	v_mov_b32_e32 v135, 0xc800
	v_writelane_b32 v163, s1, 31
	s_cselect_b64 s[0:1], -1, 0
	v_writelane_b32 v163, s0, 32
	s_cmp_eq_u32 s40, 13
	v_mov_b32_e32 v136, 0xf149f2ca
	v_writelane_b32 v163, s1, 33
	s_cselect_b64 s[0:1], -1, 0
	v_writelane_b32 v163, s0, 34
	s_cmp_eq_u32 s40, 12
	v_mov_b32_e32 v137, 0xb00
	v_writelane_b32 v163, s1, 35
	s_cselect_b64 s[0:1], -1, 0
	v_writelane_b32 v163, s0, 36
	s_cmp_eq_u32 s40, 11
	v_mov_b32_e32 v138, 0x600
	v_writelane_b32 v163, s1, 37
	s_cselect_b64 s[0:1], -1, 0
	v_writelane_b32 v163, s0, 38
	s_cmp_eq_u32 s40, 10
	v_mov_b32_e32 v139, 0xb00000
	v_writelane_b32 v163, s1, 39
	s_cselect_b64 s[0:1], -1, 0
	v_writelane_b32 v163, s0, 40
	s_cmp_eq_u32 s40, 9
	s_mov_b32 s29, 0x10000
	v_writelane_b32 v163, s1, 41
	s_cselect_b64 s[0:1], -1, 0
	v_writelane_b32 v163, s0, 42
	s_cmp_eq_u32 s40, 8
	s_mov_b32 s28, 0x20000
	v_writelane_b32 v163, s1, 43
	s_cselect_b64 s[0:1], -1, 0
	v_writelane_b32 v163, s0, 44
	s_cmp_eq_u32 s40, 7
	s_mov_b32 s27, 0x30000
	v_writelane_b32 v163, s1, 45
	s_cselect_b64 s[0:1], -1, 0
	v_writelane_b32 v163, s0, 46
	s_cmp_eq_u32 s40, 6
	s_movk_i32 s96, 0x2000
	v_writelane_b32 v163, s1, 47
	s_cselect_b64 s[0:1], -1, 0
	v_writelane_b32 v163, s0, 48
	s_cmp_eq_u32 s40, 5
	s_mov_b32 s97, 0x12000
	v_writelane_b32 v163, s1, 49
	s_cselect_b64 s[0:1], -1, 0
	v_writelane_b32 v163, s0, 50
	s_cmp_eq_u32 s40, 4
	s_movk_i32 s88, 0x7fff
	v_writelane_b32 v163, s1, 51
	s_cselect_b64 s[0:1], -1, 0
	v_writelane_b32 v163, s0, 52
	s_cmp_eq_u32 s40, 3
	s_mov_b32 s91, 0x84000
	v_writelane_b32 v163, s1, 53
	s_cselect_b64 s[0:1], -1, 0
	v_writelane_b32 v163, s0, 54
	s_cmp_eq_u32 s40, 2
	s_mov_b32 s89, 0x58000
	v_writelane_b32 v163, s1, 55
	s_cselect_b64 s[0:1], -1, 0
	v_writelane_b32 v163, s0, 56
	s_cmp_eq_u32 s40, 1
	s_mov_b32 s92, 0x2c000
	v_writelane_b32 v163, s1, 57
	s_cselect_b64 s[0:1], -1, 0
	v_writelane_b32 v163, s0, 58
	s_cmp_eq_u32 s40, 0
	s_movk_i32 s33, 0x2f00
	v_writelane_b32 v163, s1, 59
	s_cselect_b64 s[0:1], -1, 0
	v_writelane_b32 v163, s0, 60
	s_movk_i32 s26, 0x1400
	s_mov_b32 s93, 0x8000
	v_writelane_b32 v163, s1, 61
	s_lshl_b32 s0, s40, 8
	s_add_u32 s0, s84, s0
	s_addc_u32 s1, s85, 0
	s_add_u32 s4, s0, 0x1400
	s_addc_u32 s5, s1, 0
	s_add_u32 s0, s0, 0x2400
	s_addc_u32 s1, s1, 0
	v_writelane_b32 v162, s0, 0
	v_writelane_b32 v163, s4, 62
	s_mov_b32 s90, 0x3e000000
	v_writelane_b32 v162, s1, 1
	s_add_u32 s0, s84, 0x3400
	s_addc_u32 s1, s85, 0
	v_writelane_b32 v162, s0, 2
	v_writelane_b32 v163, s5, 63
	s_mov_b64 s[30:31], 0x800
	v_writelane_b32 v162, s1, 3
	s_add_u32 s0, s84, 0x3500
	s_addc_u32 s1, s85, 0
	v_writelane_b32 v162, s0, 4
	s_cmpk_lg_i32 s2, 0x60
	s_nop 0
	v_writelane_b32 v162, s1, 5
	s_cselect_b64 s[0:1], -1, 0
	v_writelane_b32 v162, s0, 6
	s_nop 1
	v_writelane_b32 v162, s1, 7
	s_lshl_b32 s0, s46, 4
	v_writelane_b32 v162, s0, 8
	s_add_u32 s0, s84, 0x3600
	v_writelane_b32 v162, s0, 9
	s_addc_u32 s0, s85, 0
	v_writelane_b32 v162, s0, 10
	s_lshl_b32 s0, s2, 7
	v_writelane_b32 v162, s0, 11
	v_writelane_b32 v162, s44, 12
	s_and_b32 s0, s46, -8
	s_ashr_i32 s35, s34, 31
	v_writelane_b32 v162, s45, 13
	v_writelane_b32 v162, s46, 14
	v_writelane_b32 v162, s47, 15
	v_writelane_b32 v162, s0, 16
	v_writelane_b32 v162, s2, 17
	s_lshl_b32 s0, s2, 4
	v_writelane_b32 v162, s0, 18
	v_readlane_b32 s0, v164, 33
	s_lshl_b64 s[94:95], s[34:35], 11
	v_readlane_b32 s14, v164, 47
	v_readlane_b32 s1, v164, 34
	v_readlane_b32 s15, v164, 48
	s_add_u32 s0, s14, 0x408
	s_addc_u32 s1, s15, 0
	v_readlane_b32 s10, v164, 43
	v_writelane_b32 v162, s0, 19
	v_readlane_b32 s11, v164, 44
	v_readlane_b32 s2, v164, 35
	v_writelane_b32 v162, s1, 20
	s_add_u32 s0, s10, 0x408
	s_addc_u32 s1, s11, 0
	v_readlane_b32 s3, v164, 36
	v_readlane_b32 s4, v164, 37
	v_readlane_b32 s5, v164, 38
	v_readlane_b32 s6, v164, 39
	v_readlane_b32 s7, v164, 40
	v_readlane_b32 s8, v164, 41
	v_readlane_b32 s9, v164, 42
	v_readlane_b32 s12, v164, 45
	v_readlane_b32 s13, v164, 46
	v_writelane_b32 v162, s0, 21
	s_nop 1
	v_writelane_b32 v162, s1, 22
	v_readlane_b32 s0, v164, 49
	v_readlane_b32 s1, v164, 50
	s_add_u32 s0, s0, 0x800
	v_writelane_b32 v162, s0, 23
	s_addc_u32 s0, s1, 0
	v_readlane_b32 s2, v164, 51
	v_writelane_b32 v162, s0, 24
	s_movk_i32 s0, 0xc38
	v_readlane_b32 s3, v164, 52
	v_writelane_b32 v162, s0, 25
	s_mov_b32 s2, s34
	v_writelane_b32 v162, s2, 26
	s_mov_b64 s[0:1], 0x1000
	v_readlane_b32 s4, v164, 53
	v_writelane_b32 v162, s3, 27
	s_lshl_b64 s[2:3], s[34:35], 12
	v_writelane_b32 v162, s2, 28
	s_mov_b32 s34, s37
	v_readlane_b32 s5, v164, 54
	v_writelane_b32 v162, s3, 29
	s_mov_b64 s[2:3], -1
	v_writelane_b32 v162, s2, 30
	v_readlane_b32 s6, v164, 55
	v_readlane_b32 s7, v164, 56
	v_writelane_b32 v162, s3, 31
	v_writelane_b32 v162, s68, 32
	v_readlane_b32 s8, v164, 57
	v_readlane_b32 s9, v164, 58
	v_writelane_b32 v162, s69, 33
	v_writelane_b32 v162, s70, 34
	v_readlane_b32 s10, v164, 59
	v_readlane_b32 s11, v164, 60
	v_readlane_b32 s12, v164, 61
	v_readlane_b32 s13, v164, 62
	v_readlane_b32 s14, v164, 63
	v_readlane_b32 s15, v163, 0
	v_writelane_b32 v162, s71, 35
	s_branch .LBB0_189
.LBB0_187:
	s_or_b64 exec, exec, s[2:3]
	s_waitcnt vmcnt(0) lgkmcnt(0)
	s_barrier
.LBB0_188:
	s_mov_b64 s[2:3], 0
	v_writelane_b32 v162, s2, 30
	s_mov_b32 s34, 1
	s_nop 0
	v_writelane_b32 v162, s3, 31
	s_movk_i32 s2, 0x880
	v_writelane_b32 v162, s2, 25
	s_nop 0
	v_readlane_b32 s2, v162, 37
	v_readlane_b32 s3, v162, 38
	s_and_b64 vcc, exec, s[2:3]
	s_cbranch_vccz .LBB0_189
	s_getpc_b64 s[98:99]

.LBB0_625:
	s_and_b32 s38, 0xffff, s36
	v_cvt_f32_u32_e32 v0, s38
	s_and_b32 s38, s3, 0xffff
	v_cvt_f32_u32_e32 v1, s38
	s_waitcnt vmcnt(5)
	v_mov_b32_e32 v8, v128
	v_rcp_iflag_f32_e32 v2, v0
	v_mov_b32_e32 v4, 0
	v_ashrrev_i32_e32 v9, 4, v8
	v_mul_f32_e32 v2, v1, v2
	v_trunc_f32_e32 v2, v2
	v_cvt_u32_f32_e32 v3, v2
	v_fma_f32 v1, -v2, v0, v1
	v_cmp_ge_f32_e64 s[38:39], |v1|, v0
	s_cmp_lg_u64 s[38:39], 0
	v_readfirstlane_b32 s38, v3
	s_addc_u32 s38, s38, 0
	s_and_b32 s39, s38, 0xffff
	s_mul_i32 s38, s38, s36
	s_sub_i32 s3, s3, s38
	s_lshl_b32 s3, s3, 6
	v_lshlrev_b32_e32 v0, 2, v8
	s_and_b32 s3, s3, 0xffc0
	v_and_b32_e32 v1, 60, v0
	v_or_b32_e32 v0, s3, v1
	v_lshlrev_b32_e32 v116, 2, v0
	s_lshl_b32 s36, s39, 6
	v_cmp_gt_u32_e32 vcc, s2, v0
	v_lshl_add_u64 v[6:7], s[24:25], 0, v[116:117]
	v_lshrrev_b32_e32 v36, 4, v128
	v_and_b32_e32 v37, 15, v128
	v_lshlrev_b32_e32 v37, 2, v37
	s_movk_i32 s50, 0x104
	v_mul_lo_u32 v41, v36, s50
	v_lshl_add_u32 v20, v37, 2, v41
	v_add_u32_e32 v21, 0x1040, v20
	v_add_u32_e32 v22, 0x2080, v20
	v_add_u32_e32 v23, 0x30c0, v20
	v_add_u32_e32 v24, 0x4200, v20
	v_add_u32_e32 v25, 0x4200, v21
	v_add_u32_e32 v26, 0x4200, v22
	v_add_u32_e32 v27, 0x4200, v23
	v_and_b32_e32 v41, 3, v128
	v_lshlrev_b32_e32 v41, 4, v41
	v_mul_lo_u32 v28, v41, s50
	v_and_b32_e32 v42, -4, v128
	v_add_u32_e32 v28, v28, v42
	v_add_u32_e32 v29, 0x400, v28
	v_add_u32_e32 v30, 0x800, v28
	v_add_u32_e32 v31, 0xc00, v28
	v_add_u32_e32 v32, 0x4200, v28
	v_add_u32_e32 v33, 0x4200, v29
	v_add_u32_e32 v34, 0x4200, v30
	v_add_u32_e32 v35, 0x4200, v31
	v_add_u32_e32 v38, s36, v36
	v_mul_lo_u32 v38, v38, s2
	v_lshlrev_b32_e32 v38, 2, v38
	s_lshl_b32 s51, s2, 6
	s_sub_u32 s52, s2, 4
	v_lshrrev_b32_e32 v39, 2, v128
	v_add_u32_e32 v39, s3, v39
	v_mul_lo_u32 v39, v39, s22
	v_add_u32_e32 v39, s36, v39
	v_add_u32_e32 v39, v41, v39
	v_lshlrev_b32_e32 v39, 1, v39
	s_lshl_b32 s53, s22, 7
	v_add_u32_e32 v40, s3, v37
	v_min_u32_e32 v40, s52, v40
	v_lshl_add_u32 v112, v40, 2, v38
	v_add_u32_e32 v113, s51, v112
	v_add_u32_e32 v114, s51, v113
	v_add_u32_e32 v115, s51, v114
	global_load_dwordx4 v[48:51], v112, s[24:25] nt
	global_load_dwordx4 v[52:55], v113, s[24:25] nt
	global_load_dwordx4 v[56:59], v114, s[24:25] nt
	global_load_dwordx4 v[60:63], v115, s[24:25] nt
	v_add_u32_e32 v40, s3, v37
	v_add_u32_e32 v40, 64, v40
	v_min_u32_e32 v40, s52, v40
	v_lshl_add_u32 v112, v40, 2, v38
	v_add_u32_e32 v113, s51, v112
	v_add_u32_e32 v114, s51, v113
	v_add_u32_e32 v115, s51, v114
	global_load_dwordx4 v[64:67], v112, s[24:25] nt
	global_load_dwordx4 v[68:71], v113, s[24:25] nt
	global_load_dwordx4 v[72:75], v114, s[24:25] nt
	global_load_dwordx4 v[76:79], v115, s[24:25] nt
	v_add_u32_e32 v40, s3, v37
	v_add_u32_e32 v40, 128, v40
	v_min_u32_e32 v40, s52, v40
	v_lshl_add_u32 v112, v40, 2, v38
	v_add_u32_e32 v113, s51, v112
	v_add_u32_e32 v114, s51, v113
	v_add_u32_e32 v115, s51, v114
	global_load_dwordx4 v[80:83], v112, s[24:25] nt
	global_load_dwordx4 v[84:87], v113, s[24:25] nt
	global_load_dwordx4 v[88:91], v114, s[24:25] nt
	global_load_dwordx4 v[92:95], v115, s[24:25] nt
	v_add_u32_e32 v40, s3, v37
	v_add_u32_e32 v40, 192, v40
	v_min_u32_e32 v40, s52, v40
	v_lshl_add_u32 v112, v40, 2, v38
	v_add_u32_e32 v113, s51, v112
	v_add_u32_e32 v114, s51, v113
	v_add_u32_e32 v115, s51, v114
	global_load_dwordx4 v[96:99], v112, s[24:25] nt
	global_load_dwordx4 v[100:103], v113, s[24:25] nt
	global_load_dwordx4 v[104:107], v114, s[24:25] nt
	global_load_dwordx4 v[108:111], v115, s[24:25] nt
	v_add_u32_e32 v40, s3, v37
	v_add_u32_e32 v40, 256, v40
	v_min_u32_e32 v40, s52, v40
	v_lshl_add_u32 v112, v40, 2, v38
	v_add_u32_e32 v113, s51, v112
	v_add_u32_e32 v114, s51, v113
	v_add_u32_e32 v115, s51, v114
	global_load_dwordx4 v[168:171], v112, s[24:25] nt
	global_load_dwordx4 v[172:175], v113, s[24:25] nt
	global_load_dwordx4 v[176:179], v114, s[24:25] nt
	global_load_dwordx4 v[180:183], v115, s[24:25] nt
	v_add_u32_e32 v40, s3, v37
	v_add_u32_e32 v40, 320, v40
	v_min_u32_e32 v40, s52, v40
	v_lshl_add_u32 v112, v40, 2, v38
	v_add_u32_e32 v113, s51, v112
	v_add_u32_e32 v114, s51, v113
	v_add_u32_e32 v115, s51, v114
	global_load_dwordx4 v[184:187], v112, s[24:25] nt
	global_load_dwordx4 v[188:191], v113, s[24:25] nt
	global_load_dwordx4 v[192:195], v114, s[24:25] nt
	global_load_dwordx4 v[196:199], v115, s[24:25] nt
	v_add_u32_e32 v40, s3, v37
	v_add_u32_e32 v40, 384, v40
	v_min_u32_e32 v40, s52, v40
	v_lshl_add_u32 v112, v40, 2, v38
	v_add_u32_e32 v113, s51, v112
	v_add_u32_e32 v114, s51, v113
	v_add_u32_e32 v115, s51, v114
	global_load_dwordx4 v[200:203], v112, s[24:25] nt
	global_load_dwordx4 v[204:207], v113, s[24:25] nt
	global_load_dwordx4 v[208:211], v114, s[24:25] nt
	global_load_dwordx4 v[212:215], v115, s[24:25] nt
	v_add_u32_e32 v40, s3, v37
	v_add_u32_e32 v40, 448, v40
	v_min_u32_e32 v40, s52, v40
	v_lshl_add_u32 v112, v40, 2, v38
	v_add_u32_e32 v113, s51, v112
	v_add_u32_e32 v114, s51, v113
	v_add_u32_e32 v115, s51, v114
	global_load_dwordx4 v[216:219], v112, s[24:25] nt
	global_load_dwordx4 v[220:223], v113, s[24:25] nt
	global_load_dwordx4 v[224:227], v114, s[24:25] nt
	global_load_dwordx4 v[228:231], v115, s[24:25] nt
	s_waitcnt vmcnt(28)
	v_add_u32_e32 v40, s3, v37
	v_cmp_gt_u32_e32 vcc, s2, v40
	s_nop 1
	v_cndmask_b32_e32 v48, 0, v48, vcc
	v_cndmask_b32_e32 v49, 0, v49, vcc
	v_cndmask_b32_e32 v50, 0, v50, vcc
	v_cndmask_b32_e32 v51, 0, v51, vcc
	v_cndmask_b32_e32 v52, 0, v52, vcc
	v_cndmask_b32_e32 v53, 0, v53, vcc
	v_cndmask_b32_e32 v54, 0, v54, vcc
	v_cndmask_b32_e32 v55, 0, v55, vcc
	v_cndmask_b32_e32 v56, 0, v56, vcc
	v_cndmask_b32_e32 v57, 0, v57, vcc
	v_cndmask_b32_e32 v58, 0, v58, vcc
	v_cndmask_b32_e32 v59, 0, v59, vcc
	v_cndmask_b32_e32 v60, 0, v60, vcc
	v_cndmask_b32_e32 v61, 0, v61, vcc
	v_cndmask_b32_e32 v62, 0, v62, vcc
	v_cndmask_b32_e32 v63, 0, v63, vcc
	ds_write2_b32 v20, v48, v49 offset1:1
	ds_write2_b32 v20, v50, v51 offset0:2 offset1:3
	ds_write2_b32 v21, v52, v53 offset1:1
	ds_write2_b32 v21, v54, v55 offset0:2 offset1:3
	ds_write2_b32 v22, v56, v57 offset1:1
	ds_write2_b32 v22, v58, v59 offset0:2 offset1:3
	ds_write2_b32 v23, v60, v61 offset1:1
	ds_write2_b32 v23, v62, v63 offset0:2 offset1:3
	s_waitcnt lgkmcnt(0)
	s_barrier
	ds_read2_b32 v[232:233], v28 offset0:0 offset1:65
	ds_read2_b32 v[234:235], v28 offset0:130 offset1:195
	ds_read2_b32 v[236:237], v29 offset0:4 offset1:69
	ds_read2_b32 v[238:239], v29 offset0:134 offset1:199
	ds_read2_b32 v[240:241], v30 offset0:8 offset1:73
	ds_read2_b32 v[242:243], v30 offset0:138 offset1:203
	ds_read2_b32 v[244:245], v31 offset0:12 offset1:77
	ds_read2_b32 v[246:247], v31 offset0:142 offset1:207
	s_waitcnt lgkmcnt(0)
	v_cvt_pk_bf16_f32 v248, v232, v233
	v_cvt_pk_bf16_f32 v249, v234, v235
	v_cvt_pk_bf16_f32 v250, v236, v237
	v_cvt_pk_bf16_f32 v251, v238, v239
	v_cvt_pk_bf16_f32 v252, v240, v241
	v_cvt_pk_bf16_f32 v253, v242, v243
	v_cvt_pk_bf16_f32 v254, v244, v245
	v_cvt_pk_bf16_f32 v255, v246, v247
	global_store_dwordx4 v39, v[248:251], s[20:21]
	global_store_dwordx4 v39, v[252:255], s[20:21] offset:16
	v_add_u32_e32 v39, s53, v39
	s_waitcnt vmcnt(26)
	v_add_u32_e32 v40, s3, v37
	v_add_u32_e32 v40, 64, v40
	v_cmp_gt_u32_e32 vcc, s2, v40
	s_nop 1
	v_cndmask_b32_e32 v64, 0, v64, vcc
	v_cndmask_b32_e32 v65, 0, v65, vcc
	v_cndmask_b32_e32 v66, 0, v66, vcc
	v_cndmask_b32_e32 v67, 0, v67, vcc
	v_cndmask_b32_e32 v68, 0, v68, vcc
	v_cndmask_b32_e32 v69, 0, v69, vcc
	v_cndmask_b32_e32 v70, 0, v70, vcc
	v_cndmask_b32_e32 v71, 0, v71, vcc
	v_cndmask_b32_e32 v72, 0, v72, vcc
	v_cndmask_b32_e32 v73, 0, v73, vcc
	v_cndmask_b32_e32 v74, 0, v74, vcc
	v_cndmask_b32_e32 v75, 0, v75, vcc
	v_cndmask_b32_e32 v76, 0, v76, vcc
	v_cndmask_b32_e32 v77, 0, v77, vcc
	v_cndmask_b32_e32 v78, 0, v78, vcc
	v_cndmask_b32_e32 v79, 0, v79, vcc
	ds_write2_b32 v24, v64, v65 offset1:1
	ds_write2_b32 v24, v66, v67 offset0:2 offset1:3
	ds_write2_b32 v25, v68, v69 offset1:1
	ds_write2_b32 v25, v70, v71 offset0:2 offset1:3
	ds_write2_b32 v26, v72, v73 offset1:1
	ds_write2_b32 v26, v74, v75 offset0:2 offset1:3
	ds_write2_b32 v27, v76, v77 offset1:1
	ds_write2_b32 v27, v78, v79 offset0:2 offset1:3
	s_waitcnt lgkmcnt(0)
	s_barrier
	ds_read2_b32 v[232:233], v32 offset0:0 offset1:65
	ds_read2_b32 v[234:235], v32 offset0:130 offset1:195
	ds_read2_b32 v[236:237], v33 offset0:4 offset1:69
	ds_read2_b32 v[238:239], v33 offset0:134 offset1:199
	ds_read2_b32 v[240:241], v34 offset0:8 offset1:73
	ds_read2_b32 v[242:243], v34 offset0:138 offset1:203
	ds_read2_b32 v[244:245], v35 offset0:12 offset1:77
	ds_read2_b32 v[246:247], v35 offset0:142 offset1:207
	s_waitcnt lgkmcnt(0)
	v_cvt_pk_bf16_f32 v248, v232, v233
	v_cvt_pk_bf16_f32 v249, v234, v235
	v_cvt_pk_bf16_f32 v250, v236, v237
	v_cvt_pk_bf16_f32 v251, v238, v239
	v_cvt_pk_bf16_f32 v252, v240, v241
	v_cvt_pk_bf16_f32 v253, v242, v243
	v_cvt_pk_bf16_f32 v254, v244, v245
	v_cvt_pk_bf16_f32 v255, v246, v247
	global_store_dwordx4 v39, v[248:251], s[20:21]
	global_store_dwordx4 v39, v[252:255], s[20:21] offset:16
	v_add_u32_e32 v39, s53, v39
	s_waitcnt vmcnt(24)
	v_add_u32_e32 v40, s3, v37
	v_add_u32_e32 v40, 128, v40
	v_cmp_gt_u32_e32 vcc, s2, v40
	s_nop 1
	v_cndmask_b32_e32 v80, 0, v80, vcc
	v_cndmask_b32_e32 v81, 0, v81, vcc
	v_cndmask_b32_e32 v82, 0, v82, vcc
	v_cndmask_b32_e32 v83, 0, v83, vcc
	v_cndmask_b32_e32 v84, 0, v84, vcc
	v_cndmask_b32_e32 v85, 0, v85, vcc
	v_cndmask_b32_e32 v86, 0, v86, vcc
	v_cndmask_b32_e32 v87, 0, v87, vcc
	v_cndmask_b32_e32 v88, 0, v88, vcc
	v_cndmask_b32_e32 v89, 0, v89, vcc
	v_cndmask_b32_e32 v90, 0, v90, vcc
	v_cndmask_b32_e32 v91, 0, v91, vcc
	v_cndmask_b32_e32 v92, 0, v92, vcc
	v_cndmask_b32_e32 v93, 0, v93, vcc
	v_cndmask_b32_e32 v94, 0, v94, vcc
	v_cndmask_b32_e32 v95, 0, v95, vcc
	ds_write2_b32 v20, v80, v81 offset1:1
	ds_write2_b32 v20, v82, v83 offset0:2 offset1:3
	ds_write2_b32 v21, v84, v85 offset1:1
	ds_write2_b32 v21, v86, v87 offset0:2 offset1:3
	ds_write2_b32 v22, v88, v89 offset1:1
	ds_write2_b32 v22, v90, v91 offset0:2 offset1:3
	ds_write2_b32 v23, v92, v93 offset1:1
	ds_write2_b32 v23, v94, v95 offset0:2 offset1:3
	s_waitcnt lgkmcnt(0)
	s_barrier
	ds_read2_b32 v[232:233], v28 offset0:0 offset1:65
	ds_read2_b32 v[234:235], v28 offset0:130 offset1:195
	ds_read2_b32 v[236:237], v29 offset0:4 offset1:69
	ds_read2_b32 v[238:239], v29 offset0:134 offset1:199
	ds_read2_b32 v[240:241], v30 offset0:8 offset1:73
	ds_read2_b32 v[242:243], v30 offset0:138 offset1:203
	ds_read2_b32 v[244:245], v31 offset0:12 offset1:77
	ds_read2_b32 v[246:247], v31 offset0:142 offset1:207
	s_waitcnt lgkmcnt(0)
	v_cvt_pk_bf16_f32 v248, v232, v233
	v_cvt_pk_bf16_f32 v249, v234, v235
	v_cvt_pk_bf16_f32 v250, v236, v237
	v_cvt_pk_bf16_f32 v251, v238, v239
	v_cvt_pk_bf16_f32 v252, v240, v241
	v_cvt_pk_bf16_f32 v253, v242, v243
	v_cvt_pk_bf16_f32 v254, v244, v245
	v_cvt_pk_bf16_f32 v255, v246, v247
	global_store_dwordx4 v39, v[248:251], s[20:21]
	global_store_dwordx4 v39, v[252:255], s[20:21] offset:16
	v_add_u32_e32 v39, s53, v39
	s_waitcnt vmcnt(22)
	v_add_u32_e32 v40, s3, v37
	v_add_u32_e32 v40, 192, v40
	v_cmp_gt_u32_e32 vcc, s2, v40
	s_nop 1
	v_cndmask_b32_e32 v96, 0, v96, vcc
	v_cndmask_b32_e32 v97, 0, v97, vcc
	v_cndmask_b32_e32 v98, 0, v98, vcc
	v_cndmask_b32_e32 v99, 0, v99, vcc
	v_cndmask_b32_e32 v100, 0, v100, vcc
	v_cndmask_b32_e32 v101, 0, v101, vcc
	v_cndmask_b32_e32 v102, 0, v102, vcc
	v_cndmask_b32_e32 v103, 0, v103, vcc
	v_cndmask_b32_e32 v104, 0, v104, vcc
	v_cndmask_b32_e32 v105, 0, v105, vcc
	v_cndmask_b32_e32 v106, 0, v106, vcc
	v_cndmask_b32_e32 v107, 0, v107, vcc
	v_cndmask_b32_e32 v108, 0, v108, vcc
	v_cndmask_b32_e32 v109, 0, v109, vcc
	v_cndmask_b32_e32 v110, 0, v110, vcc
	v_cndmask_b32_e32 v111, 0, v111, vcc
	ds_write2_b32 v24, v96, v97 offset1:1
	ds_write2_b32 v24, v98, v99 offset0:2 offset1:3
	ds_write2_b32 v25, v100, v101 offset1:1
	ds_write2_b32 v25, v102, v103 offset0:2 offset1:3
	ds_write2_b32 v26, v104, v105 offset1:1
	ds_write2_b32 v26, v106, v107 offset0:2 offset1:3
	ds_write2_b32 v27, v108, v109 offset1:1
	ds_write2_b32 v27, v110, v111 offset0:2 offset1:3
	s_waitcnt lgkmcnt(0)
	s_barrier
	ds_read2_b32 v[232:233], v32 offset0:0 offset1:65
	ds_read2_b32 v[234:235], v32 offset0:130 offset1:195
	ds_read2_b32 v[236:237], v33 offset0:4 offset1:69
	ds_read2_b32 v[238:239], v33 offset0:134 offset1:199
	ds_read2_b32 v[240:241], v34 offset0:8 offset1:73
	ds_read2_b32 v[242:243], v34 offset0:138 offset1:203
	ds_read2_b32 v[244:245], v35 offset0:12 offset1:77
	ds_read2_b32 v[246:247], v35 offset0:142 offset1:207
	s_waitcnt lgkmcnt(0)
	v_cvt_pk_bf16_f32 v248, v232, v233
	v_cvt_pk_bf16_f32 v249, v234, v235
	v_cvt_pk_bf16_f32 v250, v236, v237
	v_cvt_pk_bf16_f32 v251, v238, v239
	v_cvt_pk_bf16_f32 v252, v240, v241
	v_cvt_pk_bf16_f32 v253, v242, v243
	v_cvt_pk_bf16_f32 v254, v244, v245
	v_cvt_pk_bf16_f32 v255, v246, v247
	global_store_dwordx4 v39, v[248:251], s[20:21]
	global_store_dwordx4 v39, v[252:255], s[20:21] offset:16
	v_add_u32_e32 v39, s53, v39
	s_waitcnt vmcnt(20)
	v_add_u32_e32 v40, s3, v37
	v_add_u32_e32 v40, 256, v40
	v_cmp_gt_u32_e32 vcc, s2, v40
	s_nop 1
	v_cndmask_b32_e32 v168, 0, v168, vcc
	v_cndmask_b32_e32 v169, 0, v169, vcc
	v_cndmask_b32_e32 v170, 0, v170, vcc
	v_cndmask_b32_e32 v171, 0, v171, vcc
	v_cndmask_b32_e32 v172, 0, v172, vcc
	v_cndmask_b32_e32 v173, 0, v173, vcc
	v_cndmask_b32_e32 v174, 0, v174, vcc
	v_cndmask_b32_e32 v175, 0, v175, vcc
	v_cndmask_b32_e32 v176, 0, v176, vcc
	v_cndmask_b32_e32 v177, 0, v177, vcc
	v_cndmask_b32_e32 v178, 0, v178, vcc
	v_cndmask_b32_e32 v179, 0, v179, vcc
	v_cndmask_b32_e32 v180, 0, v180, vcc
	v_cndmask_b32_e32 v181, 0, v181, vcc
	v_cndmask_b32_e32 v182, 0, v182, vcc
	v_cndmask_b32_e32 v183, 0, v183, vcc
	ds_write2_b32 v20, v168, v169 offset1:1
	ds_write2_b32 v20, v170, v171 offset0:2 offset1:3
	ds_write2_b32 v21, v172, v173 offset1:1
	ds_write2_b32 v21, v174, v175 offset0:2 offset1:3
	ds_write2_b32 v22, v176, v177 offset1:1
	ds_write2_b32 v22, v178, v179 offset0:2 offset1:3
	ds_write2_b32 v23, v180, v181 offset1:1
	ds_write2_b32 v23, v182, v183 offset0:2 offset1:3
	s_waitcnt lgkmcnt(0)
	s_barrier
	ds_read2_b32 v[232:233], v28 offset0:0 offset1:65
	ds_read2_b32 v[234:235], v28 offset0:130 offset1:195
	ds_read2_b32 v[236:237], v29 offset0:4 offset1:69
	ds_read2_b32 v[238:239], v29 offset0:134 offset1:199
	ds_read2_b32 v[240:241], v30 offset0:8 offset1:73
	ds_read2_b32 v[242:243], v30 offset0:138 offset1:203
	ds_read2_b32 v[244:245], v31 offset0:12 offset1:77
	ds_read2_b32 v[246:247], v31 offset0:142 offset1:207
	s_waitcnt lgkmcnt(0)
	v_cvt_pk_bf16_f32 v248, v232, v233
	v_cvt_pk_bf16_f32 v249, v234, v235
	v_cvt_pk_bf16_f32 v250, v236, v237
	v_cvt_pk_bf16_f32 v251, v238, v239
	v_cvt_pk_bf16_f32 v252, v240, v241
	v_cvt_pk_bf16_f32 v253, v242, v243
	v_cvt_pk_bf16_f32 v254, v244, v245
	v_cvt_pk_bf16_f32 v255, v246, v247
	global_store_dwordx4 v39, v[248:251], s[20:21]
	global_store_dwordx4 v39, v[252:255], s[20:21] offset:16
	v_add_u32_e32 v39, s53, v39
	s_waitcnt vmcnt(18)
	v_add_u32_e32 v40, s3, v37
	v_add_u32_e32 v40, 320, v40
	v_cmp_gt_u32_e32 vcc, s2, v40
	s_nop 1
	v_cndmask_b32_e32 v184, 0, v184, vcc
	v_cndmask_b32_e32 v185, 0, v185, vcc
	v_cndmask_b32_e32 v186, 0, v186, vcc
	v_cndmask_b32_e32 v187, 0, v187, vcc
	v_cndmask_b32_e32 v188, 0, v188, vcc
	v_cndmask_b32_e32 v189, 0, v189, vcc
	v_cndmask_b32_e32 v190, 0, v190, vcc
	v_cndmask_b32_e32 v191, 0, v191, vcc
	v_cndmask_b32_e32 v192, 0, v192, vcc
	v_cndmask_b32_e32 v193, 0, v193, vcc
	v_cndmask_b32_e32 v194, 0, v194, vcc
	v_cndmask_b32_e32 v195, 0, v195, vcc
	v_cndmask_b32_e32 v196, 0, v196, vcc
	v_cndmask_b32_e32 v197, 0, v197, vcc
	v_cndmask_b32_e32 v198, 0, v198, vcc
	v_cndmask_b32_e32 v199, 0, v199, vcc
	ds_write2_b32 v24, v184, v185 offset1:1
	ds_write2_b32 v24, v186, v187 offset0:2 offset1:3
	ds_write2_b32 v25, v188, v189 offset1:1
	ds_write2_b32 v25, v190, v191 offset0:2 offset1:3
	ds_write2_b32 v26, v192, v193 offset1:1
	ds_write2_b32 v26, v194, v195 offset0:2 offset1:3
	ds_write2_b32 v27, v196, v197 offset1:1
	ds_write2_b32 v27, v198, v199 offset0:2 offset1:3
	s_waitcnt lgkmcnt(0)
	s_barrier
	ds_read2_b32 v[232:233], v32 offset0:0 offset1:65
	ds_read2_b32 v[234:235], v32 offset0:130 offset1:195
	ds_read2_b32 v[236:237], v33 offset0:4 offset1:69
	ds_read2_b32 v[238:239], v33 offset0:134 offset1:199
	ds_read2_b32 v[240:241], v34 offset0:8 offset1:73
	ds_read2_b32 v[242:243], v34 offset0:138 offset1:203
	ds_read2_b32 v[244:245], v35 offset0:12 offset1:77
	ds_read2_b32 v[246:247], v35 offset0:142 offset1:207
	s_waitcnt lgkmcnt(0)
	v_cvt_pk_bf16_f32 v248, v232, v233
	v_cvt_pk_bf16_f32 v249, v234, v235
	v_cvt_pk_bf16_f32 v250, v236, v237
	v_cvt_pk_bf16_f32 v251, v238, v239
	v_cvt_pk_bf16_f32 v252, v240, v241
	v_cvt_pk_bf16_f32 v253, v242, v243
	v_cvt_pk_bf16_f32 v254, v244, v245
	v_cvt_pk_bf16_f32 v255, v246, v247
	global_store_dwordx4 v39, v[248:251], s[20:21]
	global_store_dwordx4 v39, v[252:255], s[20:21] offset:16
	v_add_u32_e32 v39, s53, v39
	s_waitcnt vmcnt(16)
	v_add_u32_e32 v40, s3, v37
	v_add_u32_e32 v40, 384, v40
	v_cmp_gt_u32_e32 vcc, s2, v40
	s_nop 1
	v_cndmask_b32_e32 v200, 0, v200, vcc
	v_cndmask_b32_e32 v201, 0, v201, vcc
	v_cndmask_b32_e32 v202, 0, v202, vcc
	v_cndmask_b32_e32 v203, 0, v203, vcc
	v_cndmask_b32_e32 v204, 0, v204, vcc
	v_cndmask_b32_e32 v205, 0, v205, vcc
	v_cndmask_b32_e32 v206, 0, v206, vcc
	v_cndmask_b32_e32 v207, 0, v207, vcc
	v_cndmask_b32_e32 v208, 0, v208, vcc
	v_cndmask_b32_e32 v209, 0, v209, vcc
	v_cndmask_b32_e32 v210, 0, v210, vcc
	v_cndmask_b32_e32 v211, 0, v211, vcc
	v_cndmask_b32_e32 v212, 0, v212, vcc
	v_cndmask_b32_e32 v213, 0, v213, vcc
	v_cndmask_b32_e32 v214, 0, v214, vcc
	v_cndmask_b32_e32 v215, 0, v215, vcc
	ds_write2_b32 v20, v200, v201 offset1:1
	ds_write2_b32 v20, v202, v203 offset0:2 offset1:3
	ds_write2_b32 v21, v204, v205 offset1:1
	ds_write2_b32 v21, v206, v207 offset0:2 offset1:3
	ds_write2_b32 v22, v208, v209 offset1:1
	ds_write2_b32 v22, v210, v211 offset0:2 offset1:3
	ds_write2_b32 v23, v212, v213 offset1:1
	ds_write2_b32 v23, v214, v215 offset0:2 offset1:3
	s_waitcnt lgkmcnt(0)
	s_barrier
	ds_read2_b32 v[232:233], v28 offset0:0 offset1:65
	ds_read2_b32 v[234:235], v28 offset0:130 offset1:195
	ds_read2_b32 v[236:237], v29 offset0:4 offset1:69
	ds_read2_b32 v[238:239], v29 offset0:134 offset1:199
	ds_read2_b32 v[240:241], v30 offset0:8 offset1:73
	ds_read2_b32 v[242:243], v30 offset0:138 offset1:203
	ds_read2_b32 v[244:245], v31 offset0:12 offset1:77
	ds_read2_b32 v[246:247], v31 offset0:142 offset1:207
	s_waitcnt lgkmcnt(0)
	v_cvt_pk_bf16_f32 v248, v232, v233
	v_cvt_pk_bf16_f32 v249, v234, v235
	v_cvt_pk_bf16_f32 v250, v236, v237
	v_cvt_pk_bf16_f32 v251, v238, v239
	v_cvt_pk_bf16_f32 v252, v240, v241
	v_cvt_pk_bf16_f32 v253, v242, v243
	v_cvt_pk_bf16_f32 v254, v244, v245
	v_cvt_pk_bf16_f32 v255, v246, v247
	global_store_dwordx4 v39, v[248:251], s[20:21]
	global_store_dwordx4 v39, v[252:255], s[20:21] offset:16
	v_add_u32_e32 v39, s53, v39
	s_waitcnt vmcnt(14)
	v_add_u32_e32 v40, s3, v37
	v_add_u32_e32 v40, 448, v40
	v_cmp_gt_u32_e32 vcc, s2, v40
	s_nop 1
	v_cndmask_b32_e32 v216, 0, v216, vcc
	v_cndmask_b32_e32 v217, 0, v217, vcc
	v_cndmask_b32_e32 v218, 0, v218, vcc
	v_cndmask_b32_e32 v219, 0, v219, vcc
	v_cndmask_b32_e32 v220, 0, v220, vcc
	v_cndmask_b32_e32 v221, 0, v221, vcc
	v_cndmask_b32_e32 v222, 0, v222, vcc
	v_cndmask_b32_e32 v223, 0, v223, vcc
	v_cndmask_b32_e32 v224, 0, v224, vcc
	v_cndmask_b32_e32 v225, 0, v225, vcc
	v_cndmask_b32_e32 v226, 0, v226, vcc
	v_cndmask_b32_e32 v227, 0, v227, vcc
	v_cndmask_b32_e32 v228, 0, v228, vcc
	v_cndmask_b32_e32 v229, 0, v229, vcc
	v_cndmask_b32_e32 v230, 0, v230, vcc
	v_cndmask_b32_e32 v231, 0, v231, vcc
	ds_write2_b32 v24, v216, v217 offset1:1
	ds_write2_b32 v24, v218, v219 offset0:2 offset1:3
	ds_write2_b32 v25, v220, v221 offset1:1
	ds_write2_b32 v25, v222, v223 offset0:2 offset1:3
	ds_write2_b32 v26, v224, v225 offset1:1
	ds_write2_b32 v26, v226, v227 offset0:2 offset1:3
	ds_write2_b32 v27, v228, v229 offset1:1
	ds_write2_b32 v27, v230, v231 offset0:2 offset1:3
	s_waitcnt lgkmcnt(0)
	s_barrier
	ds_read2_b32 v[232:233], v32 offset0:0 offset1:65
	ds_read2_b32 v[234:235], v32 offset0:130 offset1:195
	ds_read2_b32 v[236:237], v33 offset0:4 offset1:69
	ds_read2_b32 v[238:239], v33 offset0:134 offset1:199
	ds_read2_b32 v[240:241], v34 offset0:8 offset1:73
	ds_read2_b32 v[242:243], v34 offset0:138 offset1:203
	ds_read2_b32 v[244:245], v35 offset0:12 offset1:77
	ds_read2_b32 v[246:247], v35 offset0:142 offset1:207
	s_waitcnt lgkmcnt(0)
	v_cvt_pk_bf16_f32 v248, v232, v233
	v_cvt_pk_bf16_f32 v249, v234, v235
	v_cvt_pk_bf16_f32 v250, v236, v237
	v_cvt_pk_bf16_f32 v251, v238, v239
	v_cvt_pk_bf16_f32 v252, v240, v241
	v_cvt_pk_bf16_f32 v253, v242, v243
	v_cvt_pk_bf16_f32 v254, v244, v245
	v_cvt_pk_bf16_f32 v255, v246, v247
	global_store_dwordx4 v39, v[248:251], s[20:21]
	global_store_dwordx4 v39, v[252:255], s[20:21] offset:16
	s_waitcnt lgkmcnt(0)
	s_barrier
	s_mov_b64 s[20:21], 0
	s_branch .LBB0_634

.LBB0_1122:
	s_waitcnt vmcnt(0)
	v_readlane_b32 s4, v163, 17
	v_readlane_b32 s5, v163, 18
	s_barrier
	v_lshrrev_b32_e32 v0, 6, v128
	v_readfirstlane_b32 s20, v0
	s_cmp_lg_u32 s20, 1
	s_cbranch_scc1 .Lxb11_ninv
	buffer_inv sc1
.Lxb11_ninv:
	s_barrier
	s_and_saveexec_b64 s[2:3], s[4:5]
	s_cbranch_execnz .LBB0_1123
.Lxb11_tail:
	s_getpc_b64 s[98:99]

.LBB0_1123:
	s_waitcnt vmcnt(0) lgkmcnt(0)
	ds_read_b32 v2, v117 offset:53248
	ds_read_b32 v3, v117 offset:53252
	v_readlane_b32 s4, v163, 62
	v_readlane_b32 s5, v163, 63
	v_readlane_b32 s36, v162, 60
	s_nop 1
	s_add_u32 s36, s36, 1
	s_nop 2
	v_writelane_b32 v162, s36, 60
	global_atomic_add v0, v117, v129, s[4:5] offset:64 sc0
	s_waitcnt lgkmcnt(0)
	v_mul_lo_u32 v2, v2, s36
	v_mul_lo_u32 v3, v3, s36
	v_readlane_b32 s4, v162, 2
	v_readlane_b32 s5, v162, 3
	s_waitcnt vmcnt(0)
	v_add_u32_e32 v0, 1, v0
	s_nop 0
	v_cmp_eq_u32_e32 vcc, v0, v2
	s_nop 3
	s_cbranch_vccz .Lxb11_poll
	buffer_wbl2 sc1
	s_waitcnt vmcnt(0)
	global_atomic_add v117, v129, s[4:5] offset:64

.Lxb11_spin:
	global_load_dword v0, v117, s[4:5] offset:64 sc1
	s_waitcnt vmcnt(0)
	v_cmp_ge_u32_e32 vcc, v0, v3
	s_cbranch_vccnz .Lxb11_done
	s_sleep 1
	s_add_u32 s20, s20, 1
	s_cmp_lt_u32 s20, 0x400000
	s_cbranch_scc1 .Lxb11_spin
.Lxb11_done:
	s_branch .Lxb11_tail
.LBB0_1169:
	s_endpgm
